# P4 pre-publish local scan across row groups rewritten with DPP-fused v_fmac/v_mul on copies of the inputs (same arithmetic, ~95 fewer VALU instructions per unit on the carry chain)
# speedup vs baseline: 1.0006x; 1.0006x over previous
.LBB0_464:
	s_lshl_b32 s6, s62, 7
	v_mov_b32_e32 v239, v224
	v_mov_b32_e32 v237, v225
	s_or_b32 s6, s6, s96
	s_nop 0
	v_lshl_add_u32 v238, v237, 3, s6
	s_lshl_b32 s6, s63, 8
	s_add_i32 s6, s6, s16
	v_lshl_add_u32 v171, v239, 3, s6
	v_lshlrev_b32_e32 v232, 1, v238
	v_lshlrev_b32_e32 v233, 11, v171
	v_lshlrev_b32_e32 v92, 2, v238
	v_add_u32_e32 v164, v233, v232
	v_or_b32_e32 v235, 0x1000, v233
	global_load_dwordx4 v[184:187], v92, s[2:3] offset:16
	global_load_dwordx4 v[188:191], v92, s[2:3]
	global_load_dwordx4 v[192:195], v92, s[12:13] offset:16
	global_load_dwordx4 v[196:199], v92, s[12:13]
	global_load_dwordx4 v[240:243], v92, s[36:37] offset:16
	global_load_dwordx4 v[200:203], v92, s[36:37]
	v_or_b32_e32 v234, 0x800, v233
	v_add_u32_e32 v180, v235, v232
	v_or_b32_e32 v236, 0x1800, v233
	v_add_u32_e32 v176, 0x2000, v164
	v_add_u32_e32 v172, 0x3000, v164
	v_add_u32_e32 v182, v234, v232
	global_load_dwordx4 v[244:247], v164, s[26:27]
	global_load_dwordx4 v[152:155], v182, s[26:27]
	v_add_u32_e32 v178, v236, v232
	global_load_dwordx4 v[148:151], v180, s[26:27]
	global_load_dwordx4 v[144:147], v178, s[26:27]
	v_add_u32_e32 v174, 0x2800, v164
	global_load_dwordx4 v[140:143], v176, s[26:27]
	global_load_dwordx4 v[132:135], v174, s[26:27]
	v_add_u32_e32 v170, 0x3800, v164
	global_load_dwordx4 v[112:115], v172, s[26:27]
	global_load_dwordx4 v[92:95], v170, s[26:27]
	v_and_b32_e32 v171, 0x1ff8, v171
	s_waitcnt vmcnt(0)
	v_pk_mul_f32 v[204:205], v[186:187], s[48:49] op_sel_hi:[1,0]
	v_pk_mul_f32 v[216:217], v[190:191], s[48:49] op_sel_hi:[1,0]
	v_pk_mul_f32 v[222:223], v[188:189], s[48:49] op_sel_hi:[1,0]
	v_pk_mul_f32 v[214:215], v[198:199], s[48:49] op_sel_hi:[1,0]
	v_pk_mul_f32 v[220:221], v[196:197], s[48:49] op_sel_hi:[1,0]
	v_pk_mul_f32 v[212:213], v[202:203], s[50:51] op_sel_hi:[1,0]
	v_pk_mul_f32 v[218:219], v[200:201], s[50:51] op_sel_hi:[1,0]
	v_pk_mul_f32 v[202:203], v[194:195], s[48:49] op_sel_hi:[1,0]
	v_pk_mul_f32 v[200:201], v[242:243], s[50:51] op_sel_hi:[1,0]
	v_pk_mul_f32 v[210:211], v[184:185], s[48:49] op_sel_hi:[1,0]
	v_pk_mul_f32 v[208:209], v[192:193], s[48:49] op_sel_hi:[1,0]
	v_pk_mul_f32 v[206:207], v[240:241], s[50:51] op_sel_hi:[1,0]
	v_fmamk_f32 v136, v136, 0xbfb8aa3b, v222
	v_exp_f32_e32 v136, v136
	v_fmamk_f32 v128, v128, 0xbfb8aa3b, v220
	v_fmamk_f32 v137, v137, 0xbfb8aa3b, v223
	v_exp_f32_e32 v128, v128
	v_add_f32_e32 v136, 1.0, v136
	v_rcp_f32_e32 v136, v136
	v_exp_f32_e32 v137, v137
	v_add_f32_e32 v128, 1.0, v128
	v_rcp_f32_e32 v128, v128
	v_mul_f32_e32 v136, v218, v136
	v_exp_f32_e32 v136, v136
	v_add_f32_e32 v137, 1.0, v137
	v_rcp_f32_e32 v175, v137
	v_cmp_eq_u32_e32 vcc, 0, v171
	v_fma_f32 v173, -v136, v136, 1.0
	v_sqrt_f32_e32 v173, v173
	v_fmamk_f32 v129, v129, 0xbfb8aa3b, v221
	v_exp_f32_e32 v129, v129
	v_lshlrev_b32_e32 v185, 16, v244
	v_cndmask_b32_e64 v137, v173, 1.0, vcc
	v_mul_f32_e32 v137, v128, v137
	v_mul_f32_e32 v128, v219, v175
	v_exp_f32_e32 v128, v128
	v_and_b32_e32 v187, 0xffff0000, v244
	v_mov_b32_e32 v184, v165
	v_mul_f32_e32 v186, v137, v185
	v_fma_f32 v171, -v128, v128, 1.0
	v_sqrt_f32_e32 v171, v171
	v_add_f32_e32 v129, 1.0, v129
	v_fmamk_f32 v138, v138, 0xbfb8aa3b, v216
	v_pk_fma_f32 v[184:185], v[136:137], v[184:185], v[186:187] op_sel_hi:[1,1,0]
	v_rcp_f32_e32 v129, v129
	v_cndmask_b32_e64 v137, v171, 1.0, vcc
	v_exp_f32_e32 v171, v138
	v_fmamk_f32 v130, v130, 0xbfb8aa3b, v214
	v_mul_f32_e32 v129, v129, v137
	v_exp_f32_e32 v130, v130
	v_add_f32_e32 v137, 1.0, v171
	v_rcp_f32_e32 v137, v137
	v_mov_b32_e32 v186, v165
	v_mul_f32_e32 v138, v129, v187
	v_pk_fma_f32 v[186:187], v[128:129], v[186:187], v[138:139] op_sel_hi:[1,1,0]
	v_mul_f32_e32 v129, v212, v137
	v_exp_f32_e32 v138, v129
	v_add_f32_e32 v129, 1.0, v130
	v_fmamk_f32 v130, v139, 0xbfb8aa3b, v217
	v_exp_f32_e32 v130, v130
	v_fma_f32 v137, -v138, v138, 1.0
	v_sqrt_f32_e32 v137, v137
	v_rcp_f32_e32 v129, v129
	v_add_f32_e32 v130, 1.0, v130
	v_rcp_f32_e32 v130, v130
	v_cndmask_b32_e64 v137, v137, 1.0, vcc
	v_mul_f32_e32 v139, v129, v137
	v_fmamk_f32 v124, v124, 0xbfb8aa3b, v210
	v_mul_f32_e32 v129, v213, v130
	v_exp_f32_e32 v130, v129
	v_fmamk_f32 v129, v131, 0xbfb8aa3b, v215
	v_exp_f32_e32 v129, v129
	v_exp_f32_e32 v137, v124
	v_fma_f32 v131, -v130, v130, 1.0
	v_sqrt_f32_e32 v131, v131
	v_add_f32_e32 v129, 1.0, v129
	v_rcp_f32_e32 v129, v129
	v_lshlrev_b32_e32 v189, 16, v245
	v_cndmask_b32_e64 v131, v131, 1.0, vcc
	v_and_b32_e32 v191, 0xffff0000, v245
	v_mul_f32_e32 v131, v129, v131
	v_add_f32_e32 v129, 1.0, v137
	v_rcp_f32_e32 v129, v129
	v_mov_b32_e32 v188, v165
	v_mul_f32_e32 v190, v139, v189
	v_pk_fma_f32 v[188:189], v[138:139], v[188:189], v[190:191] op_sel_hi:[1,1,0]
	v_mov_b32_e32 v190, v165
	v_mul_f32_e32 v124, v131, v191
	v_pk_fma_f32 v[190:191], v[130:131], v[190:191], v[124:125] op_sel_hi:[1,1,0]
	v_mul_f32_e32 v124, v206, v129
	v_fmamk_f32 v120, v120, 0xbfb8aa3b, v208
	v_exp_f32_e32 v124, v124
	v_fmamk_f32 v125, v125, 0xbfb8aa3b, v211
	v_exp_f32_e32 v120, v120
	v_exp_f32_e32 v125, v125
	v_fma_f32 v129, -v124, v124, 1.0
	v_sqrt_f32_e32 v129, v129
	v_add_f32_e32 v120, 1.0, v120
	v_add_f32_e32 v125, 1.0, v125
	v_rcp_f32_e32 v120, v120
	v_rcp_f32_e32 v131, v125
	v_cndmask_b32_e64 v125, v129, 1.0, vcc
	v_fmamk_f32 v121, v121, 0xbfb8aa3b, v209
	v_mul_f32_e32 v125, v120, v125
	v_mul_f32_e32 v120, v207, v131
	v_exp_f32_e32 v120, v120
	v_exp_f32_e32 v121, v121
	v_lshlrev_b32_e32 v193, 16, v246
	v_and_b32_e32 v195, 0xffff0000, v246
	v_fma_f32 v129, -v120, v120, 1.0
	v_sqrt_f32_e32 v129, v129
	v_mov_b32_e32 v192, v165
	v_mul_f32_e32 v194, v125, v193
	v_add_f32_e32 v121, 1.0, v121
	v_fmamk_f32 v126, v126, 0xbfb8aa3b, v204
	v_pk_fma_f32 v[192:193], v[124:125], v[192:193], v[194:195] op_sel_hi:[1,1,0]
	v_rcp_f32_e32 v121, v121
	v_cndmask_b32_e64 v125, v129, 1.0, vcc
	v_exp_f32_e32 v129, v126
	v_mov_b32_e32 v194, v165
	v_mul_f32_e32 v121, v121, v125
	v_mul_f32_e32 v126, v121, v195
	v_add_f32_e32 v125, 1.0, v129
	v_rcp_f32_e32 v125, v125
	v_pk_fma_f32 v[194:195], v[120:121], v[194:195], v[126:127] op_sel_hi:[1,1,0]
	v_fmamk_f32 v122, v122, 0xbfb8aa3b, v202
	v_exp_f32_e32 v129, v122
	v_mul_f32_e32 v121, v200, v125
	v_fmamk_f32 v125, v127, 0xbfb8aa3b, v205
	v_exp_f32_e32 v125, v125
	v_exp_f32_e32 v122, v121
	v_fmamk_f32 v123, v123, 0xbfb8aa3b, v203
	v_add_f32_e32 v121, 1.0, v129
	v_add_f32_e32 v125, 1.0, v125
	v_fma_f32 v126, -v122, v122, 1.0
	v_rcp_f32_e32 v125, v125
	v_sqrt_f32_e32 v126, v126
	v_exp_f32_e32 v129, v123
	v_rcp_f32_e32 v121, v121
	v_mul_f32_e32 v123, v201, v125
	v_cndmask_b32_e64 v127, v126, 1.0, vcc
	v_exp_f32_e32 v126, v123
	v_mul_f32_e32 v123, v121, v127
	v_add_f32_e32 v121, 1.0, v129
	v_rcp_f32_e32 v121, v121
	v_fma_f32 v125, -v126, v126, 1.0
	v_sqrt_f32_e32 v125, v125
	v_lshlrev_b32_e32 v197, 16, v247
	v_and_b32_e32 v199, 0xffff0000, v247
	v_mov_b32_e32 v196, v165
	v_mul_f32_e32 v198, v123, v197
	v_pk_fma_f32 v[196:197], v[122:123], v[196:197], v[198:199] op_sel_hi:[1,1,0]
	v_cndmask_b32_e64 v123, v125, 1.0, vcc
	v_mul_f32_e32 v127, v121, v123
	v_mov_b32_e32 v198, v165
	v_mul_f32_e32 v240, v127, v199
	v_pk_fma_f32 v[198:199], v[126:127], v[198:199], v[240:241] op_sel_hi:[1,1,0]
	v_fmamk_f32 v116, v116, 0xbfb8aa3b, v222
	v_exp_f32_e32 v116, v116
	v_fmamk_f32 v108, v108, 0xbfb8aa3b, v220
	v_exp_f32_e32 v108, v108
	v_fmamk_f32 v117, v117, 0xbfb8aa3b, v223
	v_add_f32_e32 v116, 1.0, v116
	v_rcp_f32_e32 v116, v116
	v_add_f32_e32 v108, 1.0, v108
	v_rcp_f32_e32 v108, v108
	v_exp_f32_e32 v121, v117
	v_mul_f32_e32 v116, v218, v116
	v_exp_f32_e32 v241, v116
	v_fmamk_f32 v109, v109, 0xbfb8aa3b, v221
	v_exp_f32_e32 v123, v109
	v_lshlrev_b32_e32 v242, 16, v153
	v_fma_f32 v116, -v241, v241, 1.0
	v_sqrt_f32_e32 v116, v116
	v_and_b32_e32 v244, 0xffff0000, v153
	v_lshlrev_b32_e32 v240, 16, v152
	v_mov_b32_e32 v117, v184
	v_mul_f32_e32 v116, v108, v116
	v_add_f32_e32 v108, 1.0, v121
	v_rcp_f32_e32 v121, v108
	v_mul_f32_e32 v108, v184, v241
	v_fmamk_f32 v110, v110, 0xbfb8aa3b, v214
	v_exp_f32_e32 v110, v110
	v_mul_f32_e32 v109, v219, v121
	v_exp_f32_e32 v153, v109
	v_pk_fma_f32 v[108:109], v[116:117], v[240:241], v[108:109] op_sel_hi:[1,1,0]
	v_and_b32_e32 v152, 0xffff0000, v152
	v_add_f32_e32 v109, 1.0, v123
	v_rcp_f32_e32 v116, v109
	v_fma_f32 v109, -v153, v153, 1.0
	v_sqrt_f32_e32 v117, v109
	v_fmamk_f32 v109, v118, 0xbfb8aa3b, v216
	v_exp_f32_e32 v118, v109
	v_add_f32_e32 v110, 1.0, v110
	v_mul_f32_e32 v116, v116, v117
	v_mov_b32_e32 v117, v186
	v_add_f32_e32 v118, 1.0, v118
	v_rcp_f32_e32 v121, v118
	v_mul_f32_e32 v118, v186, v153
	v_pk_fma_f32 v[116:117], v[116:117], v[152:153], v[118:119] op_sel_hi:[1,1,0]
	v_rcp_f32_e32 v110, v110
	v_mul_f32_e32 v121, v212, v121
	v_exp_f32_e32 v243, v121
	v_fmamk_f32 v104, v104, 0xbfb8aa3b, v210
	v_exp_f32_e32 v104, v104
	v_fmamk_f32 v111, v111, 0xbfb8aa3b, v215
	v_fma_f32 v117, -v243, v243, 1.0
	v_sqrt_f32_e32 v118, v117
	v_fmamk_f32 v117, v119, 0xbfb8aa3b, v217
	v_exp_f32_e32 v121, v117
	v_exp_f32_e32 v123, v111
	v_mul_f32_e32 v118, v110, v118
	v_add_f32_e32 v104, 1.0, v104
	v_add_f32_e32 v110, 1.0, v121
	v_rcp_f32_e32 v121, v110
	v_mov_b32_e32 v119, v188
	v_mul_f32_e32 v110, v188, v243
	v_fmamk_f32 v100, v100, 0xbfb8aa3b, v208
	v_mul_f32_e32 v111, v213, v121
	v_exp_f32_e32 v245, v111
	v_rcp_f32_e32 v121, v104
	v_pk_fma_f32 v[110:111], v[118:119], v[242:243], v[110:111] op_sel_hi:[1,1,0]
	v_exp_f32_e32 v100, v100
	v_add_f32_e32 v111, 1.0, v123
	v_rcp_f32_e32 v118, v111
	v_fma_f32 v111, -v245, v245, 1.0
	v_sqrt_f32_e32 v119, v111
	v_mul_f32_e32 v121, v206, v121
	v_exp_f32_e32 v247, v121
	v_mul_f32_e32 v104, v190, v245
	v_mul_f32_e32 v118, v118, v119
	v_mov_b32_e32 v119, v190
	v_pk_fma_f32 v[118:119], v[118:119], v[244:245], v[104:105] op_sel_hi:[1,1,0]
	v_add_f32_e32 v100, 1.0, v100
	v_fma_f32 v104, -v247, v247, 1.0
	v_fmamk_f32 v105, v105, 0xbfb8aa3b, v211
	v_rcp_f32_e32 v100, v100
	v_sqrt_f32_e32 v104, v104
	v_exp_f32_e32 v121, v105
	v_fmamk_f32 v101, v101, 0xbfb8aa3b, v209
	v_exp_f32_e32 v123, v101
	v_mul_f32_e32 v104, v100, v104
	v_add_f32_e32 v100, 1.0, v121
	v_rcp_f32_e32 v121, v100
	v_lshlrev_b32_e32 v248, 16, v155
	v_and_b32_e32 v250, 0xffff0000, v155
	v_lshlrev_b32_e32 v246, 16, v154
	v_mul_f32_e32 v101, v207, v121
	v_exp_f32_e32 v155, v101
	v_mov_b32_e32 v105, v192
	v_mul_f32_e32 v100, v192, v247
	v_pk_fma_f32 v[100:101], v[104:105], v[246:247], v[100:101] op_sel_hi:[1,1,0]
	v_fmamk_f32 v102, v102, 0xbfb8aa3b, v202
	v_add_f32_e32 v101, 1.0, v123
	v_rcp_f32_e32 v104, v101
	v_fma_f32 v101, -v155, v155, 1.0
	v_sqrt_f32_e32 v105, v101
	v_fmamk_f32 v101, v106, 0xbfb8aa3b, v204
	v_exp_f32_e32 v106, v101
	v_and_b32_e32 v154, 0xffff0000, v154
	v_mul_f32_e32 v104, v104, v105
	v_mov_b32_e32 v105, v194
	v_add_f32_e32 v106, 1.0, v106
	v_rcp_f32_e32 v106, v106
	v_exp_f32_e32 v121, v102
	v_mul_f32_e32 v102, v194, v155
	v_pk_fma_f32 v[104:105], v[104:105], v[154:155], v[102:103] op_sel_hi:[1,1,0]
	v_fmamk_f32 v103, v103, 0xbfb8aa3b, v203
	v_mul_f32_e32 v105, v200, v106
	v_exp_f32_e32 v249, v105
	v_fmamk_f32 v105, v107, 0xbfb8aa3b, v205
	v_exp_f32_e32 v106, v105
	v_add_f32_e32 v102, 1.0, v121
	v_fma_f32 v105, -v249, v249, 1.0
	v_rcp_f32_e32 v102, v102
	v_add_f32_e32 v106, 1.0, v106
	v_sqrt_f32_e32 v107, v105
	v_rcp_f32_e32 v106, v106
	v_mul_f32_e32 v109, v136, v241
	v_mul_f32_e32 v117, v128, v153
	v_mul_f32_e32 v102, v102, v107
	v_exp_f32_e32 v107, v103
	v_mul_f32_e32 v103, v201, v106
	v_exp_f32_e32 v251, v103
	v_mov_b32_e32 v103, v196
	v_add_f32_e32 v106, 1.0, v107
	v_rcp_f32_e32 v107, v106
	v_fma_f32 v106, -v251, v251, 1.0
	v_sqrt_f32_e32 v121, v106
	v_mul_f32_e32 v106, v196, v249
	v_pk_fma_f32 v[102:103], v[102:103], v[248:249], v[106:107] op_sel_hi:[1,1,0]
	v_mul_f32_e32 v152, v198, v251
	v_mul_f32_e32 v106, v107, v121
	v_mov_b32_e32 v107, v198
	v_pk_fma_f32 v[106:107], v[106:107], v[250:251], v[152:153] op_sel_hi:[1,1,0]
	v_mul_f32_e32 v111, v138, v243
	v_mul_f32_e32 v119, v130, v245
	v_mul_f32_e32 v101, v124, v247
	v_mul_f32_e32 v105, v120, v155
	v_mul_f32_e32 v103, v122, v249
	v_mul_f32_e32 v107, v126, v251
	v_fmamk_f32 v96, v96, 0xbfb8aa3b, v222
	v_exp_f32_e32 v96, v96
	v_fmamk_f32 v88, v88, 0xbfb8aa3b, v220
	v_exp_f32_e32 v88, v88
	v_fmamk_f32 v97, v97, 0xbfb8aa3b, v223
	v_add_f32_e32 v96, 1.0, v96
	v_rcp_f32_e32 v96, v96
	v_add_f32_e32 v88, 1.0, v88
	v_rcp_f32_e32 v88, v88
	v_exp_f32_e32 v121, v97
	v_mul_f32_e32 v96, v218, v96
	v_exp_f32_e32 v153, v96
	v_fmamk_f32 v89, v89, 0xbfb8aa3b, v221
	v_exp_f32_e32 v123, v89
	v_lshlrev_b32_e32 v154, 16, v149
	v_fma_f32 v96, -v153, v153, 1.0
	v_sqrt_f32_e32 v96, v96
	v_and_b32_e32 v240, 0xffff0000, v149
	v_lshlrev_b32_e32 v152, 16, v148
	v_mov_b32_e32 v97, v108
	v_mul_f32_e32 v96, v88, v96
	v_add_f32_e32 v88, 1.0, v121
	v_rcp_f32_e32 v121, v88
	v_mul_f32_e32 v88, v108, v153
	v_fmamk_f32 v90, v90, 0xbfb8aa3b, v214
	v_exp_f32_e32 v90, v90
	v_mul_f32_e32 v89, v219, v121
	v_exp_f32_e32 v149, v89
	v_pk_fma_f32 v[88:89], v[96:97], v[152:153], v[88:89] op_sel_hi:[1,1,0]
	v_and_b32_e32 v148, 0xffff0000, v148
	v_add_f32_e32 v89, 1.0, v123
	v_rcp_f32_e32 v96, v89
	v_fma_f32 v89, -v149, v149, 1.0
	v_sqrt_f32_e32 v97, v89
	v_fmamk_f32 v89, v98, 0xbfb8aa3b, v216
	v_exp_f32_e32 v98, v89
	v_add_f32_e32 v90, 1.0, v90
	v_mul_f32_e32 v96, v96, v97
	v_mov_b32_e32 v97, v116
	v_add_f32_e32 v98, 1.0, v98
	v_rcp_f32_e32 v121, v98
	v_mul_f32_e32 v98, v116, v149
	v_pk_fma_f32 v[96:97], v[96:97], v[148:149], v[98:99] op_sel_hi:[1,1,0]
	v_rcp_f32_e32 v90, v90
	v_mul_f32_e32 v121, v212, v121
	v_exp_f32_e32 v155, v121
	v_fmamk_f32 v84, v84, 0xbfb8aa3b, v210
	v_exp_f32_e32 v84, v84
	v_fmamk_f32 v91, v91, 0xbfb8aa3b, v215
	v_fma_f32 v97, -v155, v155, 1.0
	v_sqrt_f32_e32 v98, v97
	v_fmamk_f32 v97, v99, 0xbfb8aa3b, v217
	v_exp_f32_e32 v121, v97
	v_exp_f32_e32 v123, v91
	v_mul_f32_e32 v98, v90, v98
	v_add_f32_e32 v84, 1.0, v84
	v_add_f32_e32 v90, 1.0, v121
	v_rcp_f32_e32 v121, v90
	v_mov_b32_e32 v99, v110
	v_mul_f32_e32 v90, v110, v155
	v_fmamk_f32 v80, v80, 0xbfb8aa3b, v208
	v_mul_f32_e32 v91, v213, v121
	v_exp_f32_e32 v241, v91
	v_rcp_f32_e32 v121, v84
	v_pk_fma_f32 v[90:91], v[98:99], v[154:155], v[90:91] op_sel_hi:[1,1,0]
	v_exp_f32_e32 v80, v80
	v_add_f32_e32 v91, 1.0, v123
	v_rcp_f32_e32 v98, v91
	v_fma_f32 v91, -v241, v241, 1.0
	v_sqrt_f32_e32 v99, v91
	v_mul_f32_e32 v121, v206, v121
	v_exp_f32_e32 v243, v121
	v_mul_f32_e32 v84, v118, v241
	v_mul_f32_e32 v98, v98, v99
	v_mov_b32_e32 v99, v118
	v_pk_fma_f32 v[98:99], v[98:99], v[240:241], v[84:85] op_sel_hi:[1,1,0]
	v_add_f32_e32 v80, 1.0, v80
	v_fma_f32 v84, -v243, v243, 1.0
	v_fmamk_f32 v85, v85, 0xbfb8aa3b, v211
	v_rcp_f32_e32 v80, v80
	v_sqrt_f32_e32 v84, v84
	v_exp_f32_e32 v121, v85
	v_fmamk_f32 v81, v81, 0xbfb8aa3b, v209
	v_exp_f32_e32 v123, v81
	v_mul_f32_e32 v84, v80, v84
	v_add_f32_e32 v80, 1.0, v121
	v_rcp_f32_e32 v121, v80
	v_lshlrev_b32_e32 v244, 16, v151
	v_and_b32_e32 v246, 0xffff0000, v151
	v_lshlrev_b32_e32 v242, 16, v150
	v_mul_f32_e32 v81, v207, v121
	v_exp_f32_e32 v151, v81
	v_mov_b32_e32 v85, v100
	v_mul_f32_e32 v80, v100, v243
	v_pk_fma_f32 v[80:81], v[84:85], v[242:243], v[80:81] op_sel_hi:[1,1,0]
	v_fmamk_f32 v82, v82, 0xbfb8aa3b, v202
	v_add_f32_e32 v81, 1.0, v123
	v_rcp_f32_e32 v84, v81
	v_fma_f32 v81, -v151, v151, 1.0
	v_sqrt_f32_e32 v85, v81
	v_fmamk_f32 v81, v86, 0xbfb8aa3b, v204
	v_exp_f32_e32 v86, v81
	v_and_b32_e32 v150, 0xffff0000, v150
	v_mul_f32_e32 v84, v84, v85
	v_mov_b32_e32 v85, v104
	v_add_f32_e32 v86, 1.0, v86
	v_rcp_f32_e32 v86, v86
	v_exp_f32_e32 v121, v82
	v_mul_f32_e32 v82, v104, v151
	v_pk_fma_f32 v[84:85], v[84:85], v[150:151], v[82:83] op_sel_hi:[1,1,0]
	v_fmamk_f32 v83, v83, 0xbfb8aa3b, v203
	v_mul_f32_e32 v85, v200, v86
	v_exp_f32_e32 v245, v85
	v_fmamk_f32 v85, v87, 0xbfb8aa3b, v205
	v_exp_f32_e32 v86, v85
	v_add_f32_e32 v82, 1.0, v121
	v_fma_f32 v85, -v245, v245, 1.0
	v_rcp_f32_e32 v82, v82
	v_add_f32_e32 v86, 1.0, v86
	v_sqrt_f32_e32 v87, v85
	v_rcp_f32_e32 v86, v86
	v_mul_f32_e32 v89, v153, v109
	v_mul_f32_e32 v97, v149, v117
	v_mul_f32_e32 v82, v82, v87
	v_exp_f32_e32 v87, v83
	v_mul_f32_e32 v83, v201, v86
	v_exp_f32_e32 v247, v83
	v_mov_b32_e32 v83, v102
	v_add_f32_e32 v86, 1.0, v87
	v_rcp_f32_e32 v87, v86
	v_fma_f32 v86, -v247, v247, 1.0
	v_sqrt_f32_e32 v121, v86
	v_mul_f32_e32 v86, v102, v245
	v_pk_fma_f32 v[82:83], v[82:83], v[244:245], v[86:87] op_sel_hi:[1,1,0]
	v_mul_f32_e32 v148, v106, v247
	v_mul_f32_e32 v86, v87, v121
	v_mov_b32_e32 v87, v106
	v_pk_fma_f32 v[86:87], v[86:87], v[246:247], v[148:149] op_sel_hi:[1,1,0]
	v_mul_f32_e32 v91, v155, v111
	v_mul_f32_e32 v99, v241, v119
	v_mul_f32_e32 v81, v243, v101
	v_mul_f32_e32 v85, v151, v105
	v_mul_f32_e32 v83, v245, v103
	v_mul_f32_e32 v87, v247, v107
	v_fmamk_f32 v76, v76, 0xbfb8aa3b, v222
	v_exp_f32_e32 v76, v76
	v_fmamk_f32 v72, v72, 0xbfb8aa3b, v220
	v_exp_f32_e32 v72, v72
	v_fmamk_f32 v77, v77, 0xbfb8aa3b, v223
	v_add_f32_e32 v76, 1.0, v76
	v_rcp_f32_e32 v76, v76
	v_add_f32_e32 v72, 1.0, v72
	v_rcp_f32_e32 v72, v72
	v_exp_f32_e32 v121, v77
	v_mul_f32_e32 v76, v218, v76
	v_exp_f32_e32 v149, v76
	v_fmamk_f32 v73, v73, 0xbfb8aa3b, v221
	v_exp_f32_e32 v123, v73
	v_lshlrev_b32_e32 v150, 16, v145
	v_fma_f32 v76, -v149, v149, 1.0
	v_sqrt_f32_e32 v76, v76
	v_and_b32_e32 v152, 0xffff0000, v145
	v_lshlrev_b32_e32 v148, 16, v144
	v_mov_b32_e32 v77, v88
	v_mul_f32_e32 v76, v72, v76
	v_add_f32_e32 v72, 1.0, v121
	v_rcp_f32_e32 v121, v72
	v_mul_f32_e32 v72, v88, v149
	v_fmamk_f32 v74, v74, 0xbfb8aa3b, v214
	v_exp_f32_e32 v74, v74
	v_mul_f32_e32 v73, v219, v121
	v_exp_f32_e32 v145, v73
	v_pk_fma_f32 v[72:73], v[76:77], v[148:149], v[72:73] op_sel_hi:[1,1,0]
	v_and_b32_e32 v144, 0xffff0000, v144
	v_add_f32_e32 v73, 1.0, v123
	v_rcp_f32_e32 v76, v73
	v_fma_f32 v73, -v145, v145, 1.0
	v_sqrt_f32_e32 v77, v73
	v_fmamk_f32 v73, v78, 0xbfb8aa3b, v216
	v_exp_f32_e32 v78, v73
	v_add_f32_e32 v74, 1.0, v74
	v_mul_f32_e32 v76, v76, v77
	v_mov_b32_e32 v77, v96
	v_add_f32_e32 v78, 1.0, v78
	v_rcp_f32_e32 v121, v78
	v_mul_f32_e32 v78, v96, v145
	v_pk_fma_f32 v[76:77], v[76:77], v[144:145], v[78:79] op_sel_hi:[1,1,0]
	v_rcp_f32_e32 v74, v74
	v_mul_f32_e32 v121, v212, v121
	v_exp_f32_e32 v151, v121
	v_fmamk_f32 v68, v68, 0xbfb8aa3b, v210
	v_exp_f32_e32 v68, v68
	v_fmamk_f32 v75, v75, 0xbfb8aa3b, v215
	v_fma_f32 v77, -v151, v151, 1.0
	v_sqrt_f32_e32 v78, v77
	v_fmamk_f32 v77, v79, 0xbfb8aa3b, v217
	v_exp_f32_e32 v121, v77
	v_exp_f32_e32 v123, v75
	v_mul_f32_e32 v78, v74, v78
	v_add_f32_e32 v68, 1.0, v68
	v_add_f32_e32 v74, 1.0, v121
	v_rcp_f32_e32 v121, v74
	v_mov_b32_e32 v79, v90
	v_mul_f32_e32 v74, v90, v151
	v_fmamk_f32 v64, v64, 0xbfb8aa3b, v208
	v_mul_f32_e32 v75, v213, v121
	v_exp_f32_e32 v153, v75
	v_rcp_f32_e32 v121, v68
	v_pk_fma_f32 v[74:75], v[78:79], v[150:151], v[74:75] op_sel_hi:[1,1,0]
	v_exp_f32_e32 v64, v64
	v_add_f32_e32 v75, 1.0, v123
	v_rcp_f32_e32 v78, v75
	v_fma_f32 v75, -v153, v153, 1.0
	v_sqrt_f32_e32 v79, v75
	v_mul_f32_e32 v121, v206, v121
	v_exp_f32_e32 v155, v121
	v_mul_f32_e32 v68, v98, v153
	v_mul_f32_e32 v78, v78, v79
	v_mov_b32_e32 v79, v98
	v_pk_fma_f32 v[78:79], v[78:79], v[152:153], v[68:69] op_sel_hi:[1,1,0]
	v_add_f32_e32 v64, 1.0, v64
	v_fma_f32 v68, -v155, v155, 1.0
	v_fmamk_f32 v69, v69, 0xbfb8aa3b, v211
	v_rcp_f32_e32 v64, v64
	v_sqrt_f32_e32 v68, v68
	v_exp_f32_e32 v121, v69
	v_fmamk_f32 v65, v65, 0xbfb8aa3b, v209
	v_exp_f32_e32 v123, v65
	v_mul_f32_e32 v68, v64, v68
	v_add_f32_e32 v64, 1.0, v121
	v_rcp_f32_e32 v121, v64
	v_lshlrev_b32_e32 v240, 16, v147
	v_and_b32_e32 v242, 0xffff0000, v147
	v_lshlrev_b32_e32 v154, 16, v146
	v_mul_f32_e32 v65, v207, v121
	v_exp_f32_e32 v147, v65
	v_mov_b32_e32 v69, v80
	v_mul_f32_e32 v64, v80, v155
	v_pk_fma_f32 v[64:65], v[68:69], v[154:155], v[64:65] op_sel_hi:[1,1,0]
	v_fmamk_f32 v66, v66, 0xbfb8aa3b, v202
	v_add_f32_e32 v65, 1.0, v123
	v_rcp_f32_e32 v68, v65
	v_fma_f32 v65, -v147, v147, 1.0
	v_sqrt_f32_e32 v69, v65
	v_fmamk_f32 v65, v70, 0xbfb8aa3b, v204
	v_exp_f32_e32 v70, v65
	v_and_b32_e32 v146, 0xffff0000, v146
	v_mul_f32_e32 v68, v68, v69
	v_mov_b32_e32 v69, v84
	v_add_f32_e32 v70, 1.0, v70
	v_rcp_f32_e32 v70, v70
	v_exp_f32_e32 v121, v66
	v_mul_f32_e32 v66, v84, v147
	v_pk_fma_f32 v[68:69], v[68:69], v[146:147], v[66:67] op_sel_hi:[1,1,0]
	v_fmamk_f32 v67, v67, 0xbfb8aa3b, v203
	v_mul_f32_e32 v69, v200, v70
	v_exp_f32_e32 v241, v69
	v_fmamk_f32 v69, v71, 0xbfb8aa3b, v205
	v_exp_f32_e32 v70, v69
	v_add_f32_e32 v66, 1.0, v121
	v_fma_f32 v69, -v241, v241, 1.0
	v_rcp_f32_e32 v66, v66
	v_add_f32_e32 v70, 1.0, v70
	v_sqrt_f32_e32 v71, v69
	v_rcp_f32_e32 v70, v70
	v_mul_f32_e32 v73, v149, v89
	v_mul_f32_e32 v77, v145, v97
	v_mul_f32_e32 v66, v66, v71
	v_exp_f32_e32 v71, v67
	v_mul_f32_e32 v67, v201, v70
	v_exp_f32_e32 v243, v67
	v_mov_b32_e32 v67, v82
	v_add_f32_e32 v70, 1.0, v71
	v_rcp_f32_e32 v71, v70
	v_fma_f32 v70, -v243, v243, 1.0
	v_sqrt_f32_e32 v121, v70
	v_mul_f32_e32 v70, v82, v241
	v_pk_fma_f32 v[66:67], v[66:67], v[240:241], v[70:71] op_sel_hi:[1,1,0]
	v_mul_f32_e32 v144, v86, v243
	v_mul_f32_e32 v70, v71, v121
	v_mov_b32_e32 v71, v86
	v_pk_fma_f32 v[70:71], v[70:71], v[242:243], v[144:145] op_sel_hi:[1,1,0]
	v_mul_f32_e32 v75, v151, v91
	v_mul_f32_e32 v79, v153, v99
	v_mul_f32_e32 v65, v155, v81
	v_mul_f32_e32 v69, v147, v85
	v_mul_f32_e32 v67, v241, v83
	v_mul_f32_e32 v71, v243, v87
	v_fmamk_f32 v60, v60, 0xbfb8aa3b, v222
	v_exp_f32_e32 v60, v60
	v_fmamk_f32 v56, v56, 0xbfb8aa3b, v220
	v_exp_f32_e32 v56, v56
	v_fmamk_f32 v61, v61, 0xbfb8aa3b, v223
	v_add_f32_e32 v60, 1.0, v60
	v_rcp_f32_e32 v60, v60
	v_add_f32_e32 v56, 1.0, v56
	v_rcp_f32_e32 v56, v56
	v_exp_f32_e32 v121, v61
	v_mul_f32_e32 v60, v218, v60
	v_exp_f32_e32 v145, v60
	v_fmamk_f32 v57, v57, 0xbfb8aa3b, v221
	v_exp_f32_e32 v123, v57
	v_lshlrev_b32_e32 v146, 16, v141
	v_fma_f32 v60, -v145, v145, 1.0
	v_sqrt_f32_e32 v60, v60
	v_and_b32_e32 v148, 0xffff0000, v141
	v_lshlrev_b32_e32 v144, 16, v140
	v_mov_b32_e32 v61, v72
	v_mul_f32_e32 v60, v56, v60
	v_add_f32_e32 v56, 1.0, v121
	v_rcp_f32_e32 v121, v56
	v_mul_f32_e32 v56, v72, v145
	v_fmamk_f32 v58, v58, 0xbfb8aa3b, v214
	v_exp_f32_e32 v58, v58
	v_mul_f32_e32 v57, v219, v121
	v_exp_f32_e32 v141, v57
	v_pk_fma_f32 v[56:57], v[60:61], v[144:145], v[56:57] op_sel_hi:[1,1,0]
	v_and_b32_e32 v140, 0xffff0000, v140
	v_add_f32_e32 v57, 1.0, v123
	v_rcp_f32_e32 v60, v57
	v_fma_f32 v57, -v141, v141, 1.0
	v_sqrt_f32_e32 v61, v57
	v_fmamk_f32 v57, v62, 0xbfb8aa3b, v216
	v_exp_f32_e32 v62, v57
	v_add_f32_e32 v58, 1.0, v58
	v_mul_f32_e32 v60, v60, v61
	v_mov_b32_e32 v61, v76
	v_add_f32_e32 v62, 1.0, v62
	v_rcp_f32_e32 v121, v62
	v_mul_f32_e32 v62, v76, v141
	v_pk_fma_f32 v[60:61], v[60:61], v[140:141], v[62:63] op_sel_hi:[1,1,0]
	v_rcp_f32_e32 v58, v58
	v_mul_f32_e32 v121, v212, v121
	v_exp_f32_e32 v147, v121
	v_fmamk_f32 v52, v52, 0xbfb8aa3b, v210
	v_exp_f32_e32 v52, v52
	v_fmamk_f32 v59, v59, 0xbfb8aa3b, v215
	v_fma_f32 v61, -v147, v147, 1.0
	v_sqrt_f32_e32 v62, v61
	v_fmamk_f32 v61, v63, 0xbfb8aa3b, v217
	v_exp_f32_e32 v121, v61
	v_exp_f32_e32 v123, v59
	v_mul_f32_e32 v62, v58, v62
	v_add_f32_e32 v52, 1.0, v52
	v_add_f32_e32 v58, 1.0, v121
	v_rcp_f32_e32 v121, v58
	v_mov_b32_e32 v63, v74
	v_mul_f32_e32 v58, v74, v147
	v_fmamk_f32 v48, v48, 0xbfb8aa3b, v208
	v_mul_f32_e32 v59, v213, v121
	v_exp_f32_e32 v149, v59
	v_rcp_f32_e32 v121, v52
	v_pk_fma_f32 v[58:59], v[62:63], v[146:147], v[58:59] op_sel_hi:[1,1,0]
	v_exp_f32_e32 v48, v48
	v_add_f32_e32 v59, 1.0, v123
	v_rcp_f32_e32 v62, v59
	v_fma_f32 v59, -v149, v149, 1.0
	v_sqrt_f32_e32 v63, v59
	v_mul_f32_e32 v121, v206, v121
	v_exp_f32_e32 v151, v121
	v_mul_f32_e32 v52, v78, v149
	v_mul_f32_e32 v62, v62, v63
	v_mov_b32_e32 v63, v78
	v_pk_fma_f32 v[62:63], v[62:63], v[148:149], v[52:53] op_sel_hi:[1,1,0]
	v_add_f32_e32 v48, 1.0, v48
	v_fma_f32 v52, -v151, v151, 1.0
	v_fmamk_f32 v53, v53, 0xbfb8aa3b, v211
	v_rcp_f32_e32 v48, v48
	v_sqrt_f32_e32 v52, v52
	v_exp_f32_e32 v121, v53
	v_fmamk_f32 v49, v49, 0xbfb8aa3b, v209
	v_exp_f32_e32 v123, v49
	v_mul_f32_e32 v52, v48, v52
	v_add_f32_e32 v48, 1.0, v121
	v_rcp_f32_e32 v121, v48
	v_lshlrev_b32_e32 v152, 16, v143
	v_and_b32_e32 v154, 0xffff0000, v143
	v_lshlrev_b32_e32 v150, 16, v142
	v_mul_f32_e32 v49, v207, v121
	v_exp_f32_e32 v143, v49
	v_mov_b32_e32 v53, v64
	v_mul_f32_e32 v48, v64, v151
	v_pk_fma_f32 v[48:49], v[52:53], v[150:151], v[48:49] op_sel_hi:[1,1,0]
	v_fmamk_f32 v50, v50, 0xbfb8aa3b, v202
	v_add_f32_e32 v49, 1.0, v123
	v_rcp_f32_e32 v52, v49
	v_fma_f32 v49, -v143, v143, 1.0
	v_sqrt_f32_e32 v53, v49
	v_fmamk_f32 v49, v54, 0xbfb8aa3b, v204
	v_exp_f32_e32 v54, v49
	v_and_b32_e32 v142, 0xffff0000, v142
	v_mul_f32_e32 v52, v52, v53
	v_mov_b32_e32 v53, v68
	v_add_f32_e32 v54, 1.0, v54
	v_rcp_f32_e32 v54, v54
	v_exp_f32_e32 v121, v50
	v_mul_f32_e32 v50, v68, v143
	v_pk_fma_f32 v[52:53], v[52:53], v[142:143], v[50:51] op_sel_hi:[1,1,0]
	v_fmamk_f32 v51, v51, 0xbfb8aa3b, v203
	v_mul_f32_e32 v53, v200, v54
	v_exp_f32_e32 v153, v53
	v_fmamk_f32 v53, v55, 0xbfb8aa3b, v205
	v_exp_f32_e32 v54, v53
	v_add_f32_e32 v50, 1.0, v121
	v_fma_f32 v53, -v153, v153, 1.0
	v_rcp_f32_e32 v50, v50
	v_add_f32_e32 v54, 1.0, v54
	v_sqrt_f32_e32 v55, v53
	v_rcp_f32_e32 v54, v54
	v_mul_f32_e32 v57, v145, v73
	v_mul_f32_e32 v61, v141, v77
	v_mul_f32_e32 v50, v50, v55
	v_exp_f32_e32 v55, v51
	v_mul_f32_e32 v51, v201, v54
	v_exp_f32_e32 v155, v51
	v_mov_b32_e32 v51, v66
	v_add_f32_e32 v54, 1.0, v55
	v_rcp_f32_e32 v55, v54
	v_fma_f32 v54, -v155, v155, 1.0
	v_sqrt_f32_e32 v121, v54
	v_mul_f32_e32 v54, v66, v153
	v_pk_fma_f32 v[50:51], v[50:51], v[152:153], v[54:55] op_sel_hi:[1,1,0]
	v_mul_f32_e32 v140, v70, v155
	v_mul_f32_e32 v54, v55, v121
	v_mov_b32_e32 v55, v70
	v_pk_fma_f32 v[54:55], v[54:55], v[154:155], v[140:141] op_sel_hi:[1,1,0]
	v_mul_f32_e32 v59, v147, v75
	v_mul_f32_e32 v63, v149, v79
	v_mul_f32_e32 v49, v151, v65
	v_mul_f32_e32 v53, v143, v69
	v_mul_f32_e32 v51, v153, v67
	v_mul_f32_e32 v55, v155, v71
	v_fmamk_f32 v44, v44, 0xbfb8aa3b, v222
	v_exp_f32_e32 v44, v44
	v_fmamk_f32 v40, v40, 0xbfb8aa3b, v220
	v_exp_f32_e32 v40, v40
	v_fmamk_f32 v45, v45, 0xbfb8aa3b, v223
	v_add_f32_e32 v44, 1.0, v44
	v_rcp_f32_e32 v44, v44
	v_add_f32_e32 v40, 1.0, v40
	v_rcp_f32_e32 v40, v40
	v_exp_f32_e32 v121, v45
	v_mul_f32_e32 v44, v218, v44
	v_exp_f32_e32 v141, v44
	v_fmamk_f32 v41, v41, 0xbfb8aa3b, v221
	v_exp_f32_e32 v123, v41
	v_lshlrev_b32_e32 v142, 16, v133
	v_fma_f32 v44, -v141, v141, 1.0
	v_sqrt_f32_e32 v44, v44
	v_and_b32_e32 v144, 0xffff0000, v133
	v_lshlrev_b32_e32 v140, 16, v132
	v_mov_b32_e32 v45, v56
	v_mul_f32_e32 v44, v40, v44
	v_add_f32_e32 v40, 1.0, v121
	v_rcp_f32_e32 v121, v40
	v_mul_f32_e32 v40, v56, v141
	v_fmamk_f32 v42, v42, 0xbfb8aa3b, v214
	v_exp_f32_e32 v42, v42
	v_mul_f32_e32 v41, v219, v121
	v_exp_f32_e32 v133, v41
	v_pk_fma_f32 v[40:41], v[44:45], v[140:141], v[40:41] op_sel_hi:[1,1,0]
	v_and_b32_e32 v132, 0xffff0000, v132
	v_add_f32_e32 v41, 1.0, v123
	v_rcp_f32_e32 v44, v41
	v_fma_f32 v41, -v133, v133, 1.0
	v_sqrt_f32_e32 v45, v41
	v_fmamk_f32 v41, v46, 0xbfb8aa3b, v216
	v_exp_f32_e32 v46, v41
	v_add_f32_e32 v42, 1.0, v42
	v_mul_f32_e32 v44, v44, v45
	v_mov_b32_e32 v45, v60
	v_add_f32_e32 v46, 1.0, v46
	v_rcp_f32_e32 v121, v46
	v_mul_f32_e32 v46, v60, v133
	v_pk_fma_f32 v[44:45], v[44:45], v[132:133], v[46:47] op_sel_hi:[1,1,0]
	v_rcp_f32_e32 v42, v42
	v_mul_f32_e32 v121, v212, v121
	v_exp_f32_e32 v143, v121
	v_fmamk_f32 v36, v36, 0xbfb8aa3b, v210
	v_exp_f32_e32 v36, v36
	v_fmamk_f32 v43, v43, 0xbfb8aa3b, v215
	v_fma_f32 v45, -v143, v143, 1.0
	v_sqrt_f32_e32 v46, v45
	v_fmamk_f32 v45, v47, 0xbfb8aa3b, v217
	v_exp_f32_e32 v121, v45
	v_exp_f32_e32 v123, v43
	v_mul_f32_e32 v46, v42, v46
	v_add_f32_e32 v36, 1.0, v36
	v_add_f32_e32 v42, 1.0, v121
	v_rcp_f32_e32 v121, v42
	v_mov_b32_e32 v47, v58
	v_mul_f32_e32 v42, v58, v143
	v_fmamk_f32 v32, v32, 0xbfb8aa3b, v208
	v_mul_f32_e32 v43, v213, v121
	v_exp_f32_e32 v145, v43
	v_rcp_f32_e32 v121, v36
	v_pk_fma_f32 v[42:43], v[46:47], v[142:143], v[42:43] op_sel_hi:[1,1,0]
	v_exp_f32_e32 v32, v32
	v_add_f32_e32 v43, 1.0, v123
	v_rcp_f32_e32 v46, v43
	v_fma_f32 v43, -v145, v145, 1.0
	v_sqrt_f32_e32 v47, v43
	v_mul_f32_e32 v121, v206, v121
	v_exp_f32_e32 v147, v121
	v_mul_f32_e32 v36, v62, v145
	v_mul_f32_e32 v46, v46, v47
	v_mov_b32_e32 v47, v62
	v_pk_fma_f32 v[46:47], v[46:47], v[144:145], v[36:37] op_sel_hi:[1,1,0]
	v_add_f32_e32 v32, 1.0, v32
	v_fma_f32 v36, -v147, v147, 1.0
	v_fmamk_f32 v37, v37, 0xbfb8aa3b, v211
	v_rcp_f32_e32 v32, v32
	v_sqrt_f32_e32 v36, v36
	v_exp_f32_e32 v121, v37
	v_fmamk_f32 v33, v33, 0xbfb8aa3b, v209
	v_exp_f32_e32 v123, v33
	v_mul_f32_e32 v36, v32, v36
	v_add_f32_e32 v32, 1.0, v121
	v_rcp_f32_e32 v121, v32
	v_lshlrev_b32_e32 v148, 16, v135
	v_and_b32_e32 v150, 0xffff0000, v135
	v_lshlrev_b32_e32 v146, 16, v134
	v_mul_f32_e32 v33, v207, v121
	v_exp_f32_e32 v135, v33
	v_mov_b32_e32 v37, v48
	v_mul_f32_e32 v32, v48, v147
	v_pk_fma_f32 v[32:33], v[36:37], v[146:147], v[32:33] op_sel_hi:[1,1,0]
	v_fmamk_f32 v34, v34, 0xbfb8aa3b, v202
	v_add_f32_e32 v33, 1.0, v123
	v_rcp_f32_e32 v36, v33
	v_fma_f32 v33, -v135, v135, 1.0
	v_sqrt_f32_e32 v37, v33
	v_fmamk_f32 v33, v38, 0xbfb8aa3b, v204
	v_exp_f32_e32 v38, v33
	v_and_b32_e32 v134, 0xffff0000, v134
	v_mul_f32_e32 v36, v36, v37
	v_mov_b32_e32 v37, v52
	v_add_f32_e32 v38, 1.0, v38
	v_rcp_f32_e32 v38, v38
	v_exp_f32_e32 v121, v34
	v_mul_f32_e32 v34, v52, v135
	v_pk_fma_f32 v[36:37], v[36:37], v[134:135], v[34:35] op_sel_hi:[1,1,0]
	v_fmamk_f32 v35, v35, 0xbfb8aa3b, v203
	v_mul_f32_e32 v37, v200, v38
	v_exp_f32_e32 v149, v37
	v_fmamk_f32 v37, v39, 0xbfb8aa3b, v205
	v_exp_f32_e32 v38, v37
	v_add_f32_e32 v34, 1.0, v121
	v_fma_f32 v37, -v149, v149, 1.0
	v_rcp_f32_e32 v34, v34
	v_add_f32_e32 v38, 1.0, v38
	v_sqrt_f32_e32 v39, v37
	v_rcp_f32_e32 v38, v38
	v_mul_f32_e32 v41, v141, v57
	v_mul_f32_e32 v45, v133, v61
	v_mul_f32_e32 v34, v34, v39
	v_exp_f32_e32 v39, v35
	v_mul_f32_e32 v35, v201, v38
	v_exp_f32_e32 v151, v35
	v_mov_b32_e32 v35, v50
	v_add_f32_e32 v38, 1.0, v39
	v_rcp_f32_e32 v39, v38
	v_fma_f32 v38, -v151, v151, 1.0
	v_sqrt_f32_e32 v121, v38
	v_mul_f32_e32 v38, v50, v149
	v_pk_fma_f32 v[34:35], v[34:35], v[148:149], v[38:39] op_sel_hi:[1,1,0]
	v_mul_f32_e32 v132, v54, v151
	v_mul_f32_e32 v38, v39, v121
	v_mov_b32_e32 v39, v54
	v_pk_fma_f32 v[38:39], v[38:39], v[150:151], v[132:133] op_sel_hi:[1,1,0]
	v_mul_f32_e32 v43, v143, v59
	v_mul_f32_e32 v47, v145, v63
	v_mul_f32_e32 v33, v147, v49
	v_mul_f32_e32 v37, v135, v53
	v_mul_f32_e32 v35, v149, v51
	v_mul_f32_e32 v39, v151, v55
	v_fmamk_f32 v28, v28, 0xbfb8aa3b, v222
	v_lshlrev_b32_e32 v132, 16, v112
	v_and_b32_e32 v134, 0xffff0000, v112
	v_exp_f32_e32 v112, v28
	v_fmamk_f32 v29, v29, 0xbfb8aa3b, v223
	v_exp_f32_e32 v29, v29
	v_fmamk_f32 v24, v24, 0xbfb8aa3b, v220
	v_add_f32_e32 v112, 1.0, v112
	v_rcp_f32_e32 v112, v112
	v_add_f32_e32 v29, 1.0, v29
	v_rcp_f32_e32 v29, v29
	v_lshlrev_b32_e32 v28, 16, v113
	v_and_b32_e32 v140, 0xffff0000, v113
	v_exp_f32_e32 v113, v24
	v_mul_f32_e32 v24, v218, v112
	v_exp_f32_e32 v133, v24
	v_fmamk_f32 v25, v25, 0xbfb8aa3b, v221
	v_mul_f32_e32 v29, v219, v29
	v_exp_f32_e32 v25, v25
	v_exp_f32_e32 v135, v29
	v_add_f32_e32 v112, 1.0, v113
	v_fma_f32 v113, -v133, v133, 1.0
	v_rcp_f32_e32 v112, v112
	v_sqrt_f32_e32 v113, v113
	v_add_f32_e32 v25, 1.0, v25
	v_fma_f32 v29, -v135, v135, 1.0
	v_fmamk_f32 v30, v30, 0xbfb8aa3b, v216
	v_rcp_f32_e32 v25, v25
	v_sqrt_f32_e32 v29, v29
	v_exp_f32_e32 v30, v30
	v_lshlrev_b32_e32 v142, 16, v114
	v_and_b32_e32 v144, 0xffff0000, v114
	v_mul_f32_e32 v112, v112, v113
	v_mov_b32_e32 v113, v40
	v_mul_f32_e32 v114, v40, v133
	v_pk_fma_f32 v[112:113], v[112:113], v[132:133], v[114:115] op_sel_hi:[1,1,0]
	v_mul_f32_e32 v114, v25, v29
	v_add_f32_e32 v25, 1.0, v30
	v_rcp_f32_e32 v25, v25
	v_fmamk_f32 v26, v26, 0xbfb8aa3b, v214
	v_exp_f32_e32 v26, v26
	v_lshlrev_b32_e32 v24, 16, v115
	v_mul_f32_e32 v25, v212, v25
	v_exp_f32_e32 v29, v25
	v_and_b32_e32 v148, 0xffff0000, v115
	v_mov_b32_e32 v115, v44
	v_mul_f32_e32 v30, v44, v135
	v_pk_fma_f32 v[114:115], v[114:115], v[134:135], v[30:31] op_sel_hi:[1,1,0]
	v_add_f32_e32 v25, 1.0, v26
	v_fma_f32 v26, -v29, v29, 1.0
	v_fmamk_f32 v30, v31, 0xbfb8aa3b, v217
	v_rcp_f32_e32 v25, v25
	v_sqrt_f32_e32 v26, v26
	v_exp_f32_e32 v121, v30
	v_fmamk_f32 v27, v27, 0xbfb8aa3b, v215
	v_exp_f32_e32 v27, v27
	v_mul_f32_e32 v30, v25, v26
	v_add_f32_e32 v25, 1.0, v121
	v_rcp_f32_e32 v25, v25
	v_mov_b32_e32 v31, v42
	v_mul_f32_e32 v26, v42, v29
	v_fmamk_f32 v20, v20, 0xbfb8aa3b, v210
	v_mul_f32_e32 v25, v213, v25
	v_exp_f32_e32 v141, v25
	v_mul_f32_e32 v113, v133, v41
	v_pk_fma_f32 v[132:133], v[30:31], v[28:29], v[26:27] op_sel_hi:[1,1,0]
	v_add_f32_e32 v25, 1.0, v27
	v_fma_f32 v26, -v141, v141, 1.0
	v_exp_f32_e32 v20, v20
	v_rcp_f32_e32 v25, v25
	v_sqrt_f32_e32 v26, v26
	v_fmamk_f32 v16, v16, 0xbfb8aa3b, v208
	v_add_f32_e32 v20, 1.0, v20
	v_exp_f32_e32 v16, v16
	v_mul_f32_e32 v26, v25, v26
	v_rcp_f32_e32 v25, v20
	v_mov_b32_e32 v27, v46
	v_mul_f32_e32 v20, v46, v141
	v_mul_f32_e32 v115, v135, v45
	v_mul_f32_e32 v25, v206, v25
	v_exp_f32_e32 v143, v25
	v_pk_fma_f32 v[134:135], v[26:27], v[140:141], v[20:21] op_sel_hi:[1,1,0]
	v_add_f32_e32 v16, 1.0, v16
	v_fmamk_f32 v21, v21, 0xbfb8aa3b, v211
	v_fma_f32 v20, -v143, v143, 1.0
	v_rcp_f32_e32 v16, v16
	v_sqrt_f32_e32 v20, v20
	v_exp_f32_e32 v25, v21
	v_fmamk_f32 v17, v17, 0xbfb8aa3b, v209
	v_exp_f32_e32 v17, v17
	v_mul_f32_e32 v20, v16, v20
	v_add_f32_e32 v16, 1.0, v25
	v_rcp_f32_e32 v25, v16
	v_mov_b32_e32 v21, v32
	v_mul_f32_e32 v16, v32, v143
	v_mul_f32_e32 v123, v141, v47
	v_mul_f32_e32 v25, v207, v25
	v_exp_f32_e32 v145, v25
	v_pk_fma_f32 v[140:141], v[20:21], v[142:143], v[16:17] op_sel_hi:[1,1,0]
	v_fmamk_f32 v20, v22, 0xbfb8aa3b, v204
	v_exp_f32_e32 v20, v20
	v_add_f32_e32 v16, 1.0, v17
	v_fma_f32 v17, -v145, v145, 1.0
	v_rcp_f32_e32 v16, v16
	v_sqrt_f32_e32 v17, v17
	v_add_f32_e32 v20, 1.0, v20
	v_rcp_f32_e32 v20, v20
	v_fmamk_f32 v18, v18, 0xbfb8aa3b, v202
	v_mul_f32_e32 v16, v16, v17
	v_mov_b32_e32 v17, v36
	v_exp_f32_e32 v21, v18
	v_mul_f32_e32 v18, v36, v145
	v_mul_f32_e32 v125, v143, v33
	v_pk_fma_f32 v[142:143], v[16:17], v[144:145], v[18:19] op_sel_hi:[1,1,0]
	v_mul_f32_e32 v17, v200, v20
	v_exp_f32_e32 v25, v17
	v_fmamk_f32 v17, v23, 0xbfb8aa3b, v205
	v_exp_f32_e32 v17, v17
	v_add_f32_e32 v16, 1.0, v21
	v_fma_f32 v18, -v25, v25, 1.0
	v_rcp_f32_e32 v16, v16
	v_sqrt_f32_e32 v18, v18
	v_add_f32_e32 v17, 1.0, v17
	v_rcp_f32_e32 v17, v17
	v_mul_f32_e32 v127, v145, v37
	v_mul_f32_e32 v16, v16, v18
	v_fmamk_f32 v18, v19, 0xbfb8aa3b, v203
	v_exp_f32_e32 v18, v18
	v_mul_f32_e32 v17, v201, v17
	v_exp_f32_e32 v149, v17
	v_mov_b32_e32 v17, v34
	v_add_f32_e32 v18, 1.0, v18
	v_rcp_f32_e32 v19, v18
	v_fma_f32 v18, -v149, v149, 1.0
	v_sqrt_f32_e32 v20, v18
	v_mul_f32_e32 v18, v34, v25
	v_pk_fma_f32 v[144:145], v[16:17], v[24:25], v[18:19] op_sel_hi:[1,1,0]
	v_mov_b32_e32 v17, v38
	v_mul_f32_e32 v16, v19, v20
	v_mul_f32_e32 v18, v38, v149
	v_mul_f32_e32 v121, v29, v43
	v_mul_f32_e32 v129, v25, v35
	v_pk_fma_f32 v[146:147], v[16:17], v[148:149], v[18:19] op_sel_hi:[1,1,0]
	v_mul_f32_e32 v131, v149, v39
	v_fmamk_f32 v12, v12, 0xbfb8aa3b, v222
	v_exp_f32_e32 v17, v12
	v_fmamk_f32 v8, v8, 0xbfb8aa3b, v220
	v_fmac_f32_e32 v223, 0xbfb8aa3b, v13
	v_exp_f32_e32 v19, v8
	v_add_f32_e32 v17, 1.0, v17
	v_rcp_f32_e32 v17, v17
	v_exp_f32_e32 v13, v223
	v_add_f32_e32 v19, 1.0, v19
	v_rcp_f32_e32 v19, v19
	v_mul_f32_e32 v8, v218, v17
	v_exp_f32_e32 v17, v8
	v_add_f32_e32 v13, 1.0, v13
	v_rcp_f32_e32 v13, v13
	v_fmac_f32_e32 v221, 0xbfb8aa3b, v9
	v_fma_f32 v21, -v17, v17, 1.0
	v_sqrt_f32_e32 v21, v21
	v_mul_f32_e32 v13, v219, v13
	v_exp_f32_e32 v9, v221
	v_fmamk_f32 v14, v14, 0xbfb8aa3b, v216
	v_mul_f32_e32 v28, v19, v21
	v_exp_f32_e32 v19, v13
	v_add_f32_e32 v9, 1.0, v9
	v_rcp_f32_e32 v9, v9
	v_exp_f32_e32 v14, v14
	v_fma_f32 v13, -v19, v19, 1.0
	v_sqrt_f32_e32 v13, v13
	v_lshlrev_b32_e32 v16, 16, v92
	v_mov_b32_e32 v29, v112
	v_pk_mul_f32 v[28:29], v[28:29], v[16:17]
	v_mul_f32_e32 v16, v9, v13
	v_add_f32_e32 v9, 1.0, v14
	v_rcp_f32_e32 v9, v9
	v_fmamk_f32 v10, v10, 0xbfb8aa3b, v214
	v_exp_f32_e32 v10, v10
	v_and_b32_e32 v18, 0xffff0000, v92
	v_mul_f32_e32 v9, v212, v9
	v_exp_f32_e32 v13, v9
	v_mul_f32_e32 v135, v17, v113
	v_mov_b32_e32 v17, v114
	v_pk_mul_f32 v[16:17], v[16:17], v[18:19]
	v_add_f32_e32 v9, 1.0, v10
	v_fma_f32 v10, -v13, v13, 1.0
	v_fmac_f32_e32 v217, 0xbfb8aa3b, v15
	v_add_f32_e32 v137, v16, v17
	v_rcp_f32_e32 v9, v9
	v_sqrt_f32_e32 v10, v10
	v_exp_f32_e32 v16, v217
	v_fmamk_f32 v4, v4, 0xbfb8aa3b, v210
	v_exp_f32_e32 v4, v4
	v_mul_f32_e32 v14, v9, v10
	v_add_f32_e32 v9, 1.0, v16
	v_rcp_f32_e32 v9, v9
	v_add_f32_e32 v4, 1.0, v4
	v_fmac_f32_e32 v215, 0xbfb8aa3b, v11
	v_rcp_f32_e32 v4, v4
	v_mul_f32_e32 v9, v213, v9
	v_exp_f32_e32 v10, v215
	v_exp_f32_e32 v21, v9
	v_fmamk_f32 v0, v0, 0xbfb8aa3b, v208
	v_mul_f32_e32 v4, v206, v4
	v_add_f32_e32 v9, 1.0, v10
	v_fma_f32 v10, -v21, v21, 1.0
	v_exp_f32_e32 v0, v0
	v_exp_f32_e32 v23, v4
	v_rcp_f32_e32 v9, v9
	v_sqrt_f32_e32 v10, v10
	v_add_f32_e32 v0, 1.0, v0
	v_fma_f32 v4, -v23, v23, 1.0
	v_fmac_f32_e32 v211, 0xbfb8aa3b, v5
	v_mul_f32_e32 v10, v9, v10
	v_rcp_f32_e32 v0, v0
	v_sqrt_f32_e32 v4, v4
	v_exp_f32_e32 v9, v211
	v_lshlrev_b32_e32 v22, 16, v94
	v_mov_b32_e32 v5, v140
	v_mul_f32_e32 v4, v0, v4
	v_add_f32_e32 v0, 1.0, v9
	v_rcp_f32_e32 v0, v0
	v_fmac_f32_e32 v209, 0xbfb8aa3b, v1
	v_pk_mul_f32 v[4:5], v[4:5], v[22:23]
	v_exp_f32_e32 v1, v209
	v_mul_f32_e32 v0, v207, v0
	v_exp_f32_e32 v25, v0
	v_add_f32_e32 v147, v4, v5
	v_fmamk_f32 v4, v6, 0xbfb8aa3b, v204
	v_exp_f32_e32 v4, v4
	v_add_f32_e32 v0, 1.0, v1
	v_fma_f32 v1, -v25, v25, 1.0
	v_rcp_f32_e32 v0, v0
	v_sqrt_f32_e32 v1, v1
	v_add_f32_e32 v4, 1.0, v4
	v_rcp_f32_e32 v4, v4
	v_and_b32_e32 v24, 0xffff0000, v94
	v_mul_f32_e32 v0, v0, v1
	v_mov_b32_e32 v1, v142
	v_pk_mul_f32 v[0:1], v[0:1], v[24:25]
	v_fmac_f32_e32 v205, 0xbfb8aa3b, v7
	v_add_f32_e32 v187, v0, v1
	v_mul_f32_e32 v1, v200, v4
	v_fmamk_f32 v2, v2, 0xbfb8aa3b, v202
	v_exp_f32_e32 v9, v1
	v_exp_f32_e32 v1, v205
	v_exp_f32_e32 v2, v2
	v_fmac_f32_e32 v203, 0xbfb8aa3b, v3
	v_lshlrev_b32_e32 v8, 16, v95
	v_add_f32_e32 v1, 1.0, v1
	v_add_f32_e32 v0, 1.0, v2
	v_fma_f32 v2, -v9, v9, 1.0
	v_rcp_f32_e32 v1, v1
	v_rcp_f32_e32 v0, v0
	v_sqrt_f32_e32 v2, v2
	v_lshlrev_b32_e32 v12, 16, v93
	v_mul_f32_e32 v1, v201, v1
	v_exp_f32_e32 v27, v1
	v_mul_f32_e32 v0, v0, v2
	v_exp_f32_e32 v2, v203
	v_mov_b32_e32 v1, v144
	v_fma_f32 v3, -v27, v27, 1.0
	v_sqrt_f32_e32 v3, v3
	v_add_f32_e32 v2, 1.0, v2
	v_rcp_f32_e32 v2, v2
	v_pk_mul_f32 v[0:1], v[0:1], v[8:9]
	v_and_b32_e32 v20, 0xffff0000, v93
	v_and_b32_e32 v26, 0xffff0000, v95
	v_mov_b32_e32 v15, v132
	v_mov_b32_e32 v11, v134
	v_add_f32_e32 v193, v0, v1
	v_mul_f32_e32 v0, v2, v3
	v_mov_b32_e32 v1, v146
	v_pk_mul_f32 v[14:15], v[14:15], v[12:13]
	v_pk_mul_f32 v[10:11], v[10:11], v[20:21]
	v_pk_mul_f32 v[0:1], v[0:1], v[26:27]
	v_add_f32_e32 v133, v28, v29
	v_mul_f32_e32 v141, v19, v115
	v_add_f32_e32 v139, v14, v15
	v_mul_f32_e32 v143, v13, v121
	v_add_f32_e32 v145, v10, v11
	v_mul_f32_e32 v185, v21, v123
	v_mul_f32_e32 v189, v23, v125
	v_mul_f32_e32 v191, v25, v127
	v_mul_f32_e32 v197, v9, v129
	v_add_f32_e32 v195, v0, v1
	v_mul_f32_e32 v199, v27, v131
	v_mov_b32_e32 v0, v135
	v_mov_b32_e32 v17, v133
	v_mov_b32_e32 v2, v141
	v_mov_b32_e32 v19, v137
	v_mov_b32_e32 v4, v143
	v_mov_b32_e32 v21, v139
	v_mov_b32_e32 v6, v185
	v_mov_b32_e32 v23, v145
	v_mov_b32_e32 v8, v189
	v_mov_b32_e32 v25, v147
	v_mov_b32_e32 v10, v191
	v_mov_b32_e32 v27, v187
	v_mov_b32_e32 v12, v197
	v_mov_b32_e32 v31, v193
	v_mov_b32_e32 v14, v199
	v_mov_b32_e32 v205, v195
	v_fmac_f32_dpp v17, v17, v0 row_shr:1 row_mask:0xf bank_mask:0xf
	v_fmac_f32_dpp v19, v19, v2 row_shr:1 row_mask:0xf bank_mask:0xf
	v_fmac_f32_dpp v21, v21, v4 row_shr:1 row_mask:0xf bank_mask:0xf
	v_fmac_f32_dpp v23, v23, v6 row_shr:1 row_mask:0xf bank_mask:0xf
	v_fmac_f32_dpp v25, v25, v8 row_shr:1 row_mask:0xf bank_mask:0xf
	v_fmac_f32_dpp v27, v27, v10 row_shr:1 row_mask:0xf bank_mask:0xf
	v_fmac_f32_dpp v31, v31, v12 row_shr:1 row_mask:0xf bank_mask:0xf
	v_fmac_f32_dpp v205, v205, v14 row_shr:1 row_mask:0xf bank_mask:0xf
	v_mul_f32_dpp v0, v0, v0 row_shr:1 row_mask:0xf bank_mask:0xf
	v_mul_f32_dpp v2, v2, v2 row_shr:1 row_mask:0xf bank_mask:0xf
	v_mul_f32_dpp v4, v4, v4 row_shr:1 row_mask:0xf bank_mask:0xf
	v_mul_f32_dpp v6, v6, v6 row_shr:1 row_mask:0xf bank_mask:0xf
	v_mul_f32_dpp v8, v8, v8 row_shr:1 row_mask:0xf bank_mask:0xf
	v_mul_f32_dpp v10, v10, v10 row_shr:1 row_mask:0xf bank_mask:0xf
	v_mul_f32_dpp v12, v12, v12 row_shr:1 row_mask:0xf bank_mask:0xf
	v_mul_f32_dpp v14, v14, v14 row_shr:1 row_mask:0xf bank_mask:0xf
	v_fmac_f32_dpp v17, v17, v0 row_shr:2 row_mask:0xf bank_mask:0xf
	v_fmac_f32_dpp v19, v19, v2 row_shr:2 row_mask:0xf bank_mask:0xf
	v_fmac_f32_dpp v21, v21, v4 row_shr:2 row_mask:0xf bank_mask:0xf
	v_fmac_f32_dpp v23, v23, v6 row_shr:2 row_mask:0xf bank_mask:0xf
	v_fmac_f32_dpp v25, v25, v8 row_shr:2 row_mask:0xf bank_mask:0xf
	v_fmac_f32_dpp v27, v27, v10 row_shr:2 row_mask:0xf bank_mask:0xf
	v_fmac_f32_dpp v31, v31, v12 row_shr:2 row_mask:0xf bank_mask:0xf
	v_fmac_f32_dpp v205, v205, v14 row_shr:2 row_mask:0xf bank_mask:0xf
	v_mul_f32_dpp v0, v0, v0 row_shr:2 row_mask:0xf bank_mask:0xf
	v_mul_f32_dpp v2, v2, v2 row_shr:2 row_mask:0xf bank_mask:0xf
	v_mul_f32_dpp v4, v4, v4 row_shr:2 row_mask:0xf bank_mask:0xf
	v_mul_f32_dpp v6, v6, v6 row_shr:2 row_mask:0xf bank_mask:0xf
	v_mul_f32_dpp v8, v8, v8 row_shr:2 row_mask:0xf bank_mask:0xf
	v_mul_f32_dpp v10, v10, v10 row_shr:2 row_mask:0xf bank_mask:0xf
	v_mul_f32_dpp v12, v12, v12 row_shr:2 row_mask:0xf bank_mask:0xf
	v_mul_f32_dpp v14, v14, v14 row_shr:2 row_mask:0xf bank_mask:0xf
	v_fmac_f32_dpp v17, v17, v0 row_shr:4 row_mask:0xf bank_mask:0xf
	v_fmac_f32_dpp v19, v19, v2 row_shr:4 row_mask:0xf bank_mask:0xf
	v_fmac_f32_dpp v21, v21, v4 row_shr:4 row_mask:0xf bank_mask:0xf
	v_fmac_f32_dpp v23, v23, v6 row_shr:4 row_mask:0xf bank_mask:0xf
	v_fmac_f32_dpp v25, v25, v8 row_shr:4 row_mask:0xf bank_mask:0xf
	v_fmac_f32_dpp v27, v27, v10 row_shr:4 row_mask:0xf bank_mask:0xf
	v_fmac_f32_dpp v31, v31, v12 row_shr:4 row_mask:0xf bank_mask:0xf
	v_fmac_f32_dpp v205, v205, v14 row_shr:4 row_mask:0xf bank_mask:0xf
	v_mul_f32_dpp v0, v0, v0 row_shr:4 row_mask:0xf bank_mask:0xf
	v_mul_f32_dpp v2, v2, v2 row_shr:4 row_mask:0xf bank_mask:0xf
	v_mul_f32_dpp v4, v4, v4 row_shr:4 row_mask:0xf bank_mask:0xf
	v_mul_f32_dpp v6, v6, v6 row_shr:4 row_mask:0xf bank_mask:0xf
	v_mul_f32_dpp v8, v8, v8 row_shr:4 row_mask:0xf bank_mask:0xf
	v_mul_f32_dpp v10, v10, v10 row_shr:4 row_mask:0xf bank_mask:0xf
	v_mul_f32_dpp v12, v12, v12 row_shr:4 row_mask:0xf bank_mask:0xf
	v_mul_f32_dpp v14, v14, v14 row_shr:4 row_mask:0xf bank_mask:0xf
	v_mul_f32_dpp v1, v17, v0 row_shr:8 row_mask:0xf bank_mask:0xf bound_ctrl:1
	v_mul_f32_dpp v3, v19, v2 row_shr:8 row_mask:0xf bank_mask:0xf bound_ctrl:1
	v_mul_f32_dpp v5, v21, v4 row_shr:8 row_mask:0xf bank_mask:0xf bound_ctrl:1
	v_mul_f32_dpp v7, v23, v6 row_shr:8 row_mask:0xf bank_mask:0xf bound_ctrl:1
	v_mul_f32_dpp v9, v25, v8 row_shr:8 row_mask:0xf bank_mask:0xf bound_ctrl:1
	v_mul_f32_dpp v11, v27, v10 row_shr:8 row_mask:0xf bank_mask:0xf bound_ctrl:1
	v_mul_f32_dpp v13, v31, v12 row_shr:8 row_mask:0xf bank_mask:0xf bound_ctrl:1
	v_mul_f32_dpp v15, v205, v14 row_shr:8 row_mask:0xf bank_mask:0xf bound_ctrl:1
	v_mul_f32_dpp v0, v0, v0 row_shr:8 row_mask:0xf bank_mask:0xf
	v_mul_f32_dpp v2, v2, v2 row_shr:8 row_mask:0xf bank_mask:0xf
	v_mul_f32_dpp v4, v4, v4 row_shr:8 row_mask:0xf bank_mask:0xf
	v_mul_f32_dpp v6, v6, v6 row_shr:8 row_mask:0xf bank_mask:0xf
	v_mul_f32_dpp v8, v8, v8 row_shr:8 row_mask:0xf bank_mask:0xf
	v_mul_f32_dpp v10, v10, v10 row_shr:8 row_mask:0xf bank_mask:0xf
	v_mul_f32_dpp v12, v12, v12 row_shr:8 row_mask:0xf bank_mask:0xf
	v_mul_f32_dpp v14, v14, v14 row_shr:8 row_mask:0xf bank_mask:0xf
	v_add_f32_e32 v17, v1, v17
	v_add_f32_e32 v19, v3, v19
	v_add_f32_e32 v21, v5, v21
	v_add_f32_e32 v23, v7, v23
	v_add_f32_e32 v25, v9, v25
	v_add_f32_e32 v27, v11, v27
	v_add_f32_e32 v31, v13, v31
	v_add_f32_e32 v205, v15, v205
	v_mov_b32_e32 v93, 1.0
	v_mov_b32_e32 v92, 0
	v_mov_b32_e32 v95, 1.0
	v_mov_b32_e32 v94, 0
	v_mov_b32_e32 v149, 1.0
	v_mov_b32_e32 v148, 0
	v_mov_b32_e32 v151, 1.0
	v_mov_b32_e32 v150, 0
	v_mov_b32_e32 v153, 1.0
	v_mov_b32_e32 v152, 0
	v_mov_b32_e32 v155, 1.0
	v_mov_b32_e32 v154, 0
	v_mov_b32_e32 v201, 1.0
	v_mov_b32_e32 v200, 0
	v_mov_b32_e32 v203, 1.0
	v_mov_b32_e32 v202, 0
	v_lshlrev_b32_e32 v1, 6, v237
	v_cmp_eq_u32_e64 s[8:9], 15, v239
	v_mov_b32_dpp v93, v0 row_shr:1 row_mask:0xf bank_mask:0xf
	v_mov_b32_dpp v92, v17 row_shr:1 row_mask:0xf bank_mask:0xf
	v_mov_b32_dpp v95, v2 row_shr:1 row_mask:0xf bank_mask:0xf
	v_mov_b32_dpp v94, v19 row_shr:1 row_mask:0xf bank_mask:0xf
	v_mov_b32_dpp v149, v4 row_shr:1 row_mask:0xf bank_mask:0xf
	v_mov_b32_dpp v148, v21 row_shr:1 row_mask:0xf bank_mask:0xf
	v_mov_b32_dpp v151, v6 row_shr:1 row_mask:0xf bank_mask:0xf
	v_mov_b32_dpp v150, v23 row_shr:1 row_mask:0xf bank_mask:0xf
	v_mov_b32_dpp v153, v8 row_shr:1 row_mask:0xf bank_mask:0xf
	v_mov_b32_dpp v152, v25 row_shr:1 row_mask:0xf bank_mask:0xf
	v_mov_b32_dpp v155, v10 row_shr:1 row_mask:0xf bank_mask:0xf
	v_mov_b32_dpp v154, v27 row_shr:1 row_mask:0xf bank_mask:0xf
	v_mov_b32_dpp v201, v12 row_shr:1 row_mask:0xf bank_mask:0xf
	v_mov_b32_dpp v200, v31 row_shr:1 row_mask:0xf bank_mask:0xf
	v_mov_b32_dpp v203, v14 row_shr:1 row_mask:0xf bank_mask:0xf
	v_mov_b32_dpp v202, v205 row_shr:1 row_mask:0xf bank_mask:0xf
	s_and_b64 s[20:21], s[46:47], s[8:9]
	v_add_u32_e32 v171, s17, v1
	s_and_saveexec_b64 s[6:7], s[20:21]
	s_cbranch_execz .LBB0_466
	v_mov_b32_e32 v1, v17
	v_mov_b32_e32 v3, v19
	v_mov_b32_e32 v5, v21
	v_mov_b32_e32 v7, v23
	v_mov_b32_e32 v9, v25
	v_mov_b32_e32 v11, v27
	v_mov_b32_e32 v13, v31
	v_mov_b32_e32 v15, v205
	ds_write_b128 v171, v[0:3]
	ds_write_b128 v171, v[4:7] offset:16
	ds_write_b128 v171, v[8:11] offset:32
	ds_write_b128 v171, v[12:15] offset:48
